# v29 + LN nt hints + kv-latent transposed-V epilogue loads hoisted + counted lgkmcnt waits in the attention QK bursts
# baseline (speedup 1.0000x reference)
; #define LAS __attribute__((address_space(3)))
; __device__ __forceinline__ f32x2 pk_sub(f32x2 a, f32x2 b) { f32x2 r; asm("v_pk_add_f32 %0, %1, %2 neg_lo:[0,1] neg_hi:[0,1]" : "=v"(r) : "v"(a), "v"(b)); return r; }
; template <int TYPE  >
; __device__ __forceinline__ void attn_item(const Params& P, const int b, const int h, const int qt, LAS unsigned char* lds) {
;     ...
;                 if (TYPE == 1) { const LAS float* fb = (const LAS float*)(lds + so + KREG + VREG + wid * 256) + 8 * hh;
; #pragma unroll
;                     for (int j = 0; j < 8; ++j) {
;                         const f32x2 b0 = *(const LAS f32x2*)(fb + 16 * (j >> 2) + 2 * (j & 3)), b1 = *(const LAS f32x2*)(fb + 32 + 16 * (j >> 2) + 2 * (j & 3));
;                         const f32x2 x0 = pk_sub((f32x2){s0[2 * j], s0[2 * j + 1]}, b0), x1 = pk_sub((f32x2){s1[2 * j], s1[2 * j + 1]}, b1);
;                         s0[2 * j] = x0[0]; s0[2 * j + 1] = x0[1]; s1[2 * j] = x1[0]; s1[2 * j + 1] = x1[1]; }
;                     if (diag) {
; #pragma unroll
;                         for (int i = 0; i < 16; ++i) { const int key = key0 + 16 * (i >> 3) + (i & 7); if (key > tq) s0[i] = -1e30f; if (key + 32 > tq) s1[i] = -1e30f; } } }
.LBB0_1107:
	v_add_u32_e32 v0, s29, v184
	v_add_u32_e32 v6, 0, v0
	v_xad_u32 v14, v0, 32, 0
	ds_read_b128 v[2:5], v6
	ds_read_b128 v[6:9], v6 offset:8192
	ds_read_b128 v[10:13], v14
	ds_read_b128 v[144:147], v14 offset:8192
	v_xad_u32 v14, v0, 64, 0
	ds_read_b128 v[158:161], v14
	ds_read_b128 v[176:179], v14 offset:8192
	v_xor_b32_e32 v14, 0x60, v0
	v_add_u32_e32 v14, 0, v14
	ds_read_b128 v[188:191], v14
	ds_read_b128 v[192:195], v14 offset:8192
	v_xor_b32_e32 v14, 0x80, v0
	v_add_u32_e32 v14, 0, v14
	ds_read_b128 v[196:199], v14
	ds_read_b128 v[200:203], v14 offset:8192
	v_xor_b32_e32 v14, 0xa0, v0
	v_add_u32_e32 v14, 0, v14
	ds_read_b128 v[204:207], v14
	ds_read_b128 v[226:229], v14 offset:8192
	v_xor_b32_e32 v14, 0xc0, v0
	v_xor_b32_e32 v0, 0xe0, v0
	v_add_u32_e32 v14, 0, v14
	v_add_u32_e32 v0, 0, v0
	ds_read_b128 v[230:233], v14
	ds_read_b128 v[234:237], v14 offset:8192
	ds_read_b128 v[238:241], v0
	ds_read_b128 v[242:245], v0 offset:8192
	s_setprio 1
	s_waitcnt lgkmcnt(14)
	v_mfma_f32_32x32x16_bf16 v[80:95], v[2:5], v[112:115], 0
	v_mfma_f32_32x32x16_bf16 v[96:111], v[6:9], v[112:115], 0
	s_waitcnt lgkmcnt(12)
	v_mfma_f32_32x32x16_bf16 v[80:95], v[10:13], v[116:119], v[80:95]
	v_mfma_f32_32x32x16_bf16 v[96:111], v[144:147], v[116:119], v[96:111]
	s_waitcnt lgkmcnt(10)
	v_mfma_f32_32x32x16_bf16 v[80:95], v[158:161], v[120:123], v[80:95]
	v_mfma_f32_32x32x16_bf16 v[96:111], v[176:179], v[120:123], v[96:111]
	s_waitcnt lgkmcnt(8)
	v_mfma_f32_32x32x16_bf16 v[80:95], v[188:191], v[124:127], v[80:95]
	v_mfma_f32_32x32x16_bf16 v[96:111], v[192:195], v[124:127], v[96:111]
	s_setprio 0
	s_setprio 1
	s_waitcnt lgkmcnt(6)
	v_mfma_f32_32x32x16_bf16 v[80:95], v[196:199], v[128:131], v[80:95]
	v_mfma_f32_32x32x16_bf16 v[96:111], v[200:203], v[128:131], v[96:111]
	s_waitcnt lgkmcnt(4)
	v_mfma_f32_32x32x16_bf16 v[80:95], v[204:207], v[132:135], v[80:95]
	v_mfma_f32_32x32x16_bf16 v[96:111], v[226:229], v[132:135], v[96:111]
	s_waitcnt lgkmcnt(2)
	v_mfma_f32_32x32x16_bf16 v[80:95], v[230:233], v[136:139], v[80:95]
	v_mfma_f32_32x32x16_bf16 v[96:111], v[234:237], v[136:139], v[96:111]
	s_waitcnt lgkmcnt(0)
	v_mfma_f32_32x32x16_bf16 v[80:95], v[238:241], v[140:143], v[80:95]
	v_mfma_f32_32x32x16_bf16 v[96:111], v[242:245], v[140:143], v[96:111]
	s_setprio 0
	v_add_u32_e32 v10, s29, v186
	v_add_u32_e32 v0, s29, v185
	v_xor_b32_e32 v11, 64, v10
	v_add_u32_e32 v0, 0, v0
	v_xor_b32_e32 v2, 32, v10
	v_add_u32_e32 v188, 0, v11
	v_xor_b32_e32 v10, 0x60, v10
	s_nop 7
	s_nop 7
	s_nop 3
	v_add_u32_e32 v187, 0, v2
	ds_read_b128 v[6:9], v0 offset:16384
	ds_read_b128 v[2:5], v187
	v_add_u32_e32 v189, 0, v10
	ds_read_b128 v[144:147], v188
	ds_read_b128 v[10:13], v189
	s_cmp_lg_u32 s26, s17
	s_cbranch_scc1 .LBB0_1109
	v_cndmask_b32_e64 v95, v223, v95, s[38:39]
	v_cndmask_b32_e64 v94, v223, v94, s[42:43]
	v_cndmask_b32_e64 v93, v223, v93, s[44:45]
	v_cndmask_b32_e64 v92, v223, v92, s[46:47]
	v_cndmask_b32_e64 v91, v223, v91, s[48:49]
	v_cndmask_b32_e64 v90, v223, v90, s[50:51]
	v_cndmask_b32_e64 v89, v223, v89, s[52:53]
	v_cndmask_b32_e64 v88, v223, v88, s[54:55]
	v_cndmask_b32_e64 v87, v223, v87, s[56:57]
	v_cndmask_b32_e64 v86, v223, v86, s[58:59]
	v_cndmask_b32_e64 v85, v223, v85, s[60:61]
	v_cndmask_b32_e64 v84, v223, v84, s[62:63]
	v_cndmask_b32_e64 v83, v223, v83, s[4:5]
	v_cndmask_b32_e64 v82, v223, v82, s[64:65]
	v_cndmask_b32_e64 v81, v223, v81, s[66:67]
	v_cndmask_b32_e64 v80, v223, v80, s[68:69]
	v_cndmask_b32_e64 v111, v223, v111, s[40:41]
	v_cndmask_b32_e64 v110, v223, v110, s[70:71]
	v_cndmask_b32_e64 v109, v223, v109, s[72:73]
	v_cndmask_b32_e64 v108, v223, v108, s[6:7]
	v_cndmask_b32_e64 v107, v223, v107, s[74:75]
	v_cndmask_b32_e64 v106, v223, v106, s[76:77]
	v_cndmask_b32_e64 v105, v223, v105, s[78:79]
	v_cndmask_b32_e64 v104, v223, v104, s[80:81]
	v_cndmask_b32_e64 v103, v223, v103, s[82:83]
	v_cndmask_b32_e64 v102, v223, v102, s[84:85]
	v_cndmask_b32_e64 v101, v223, v101, s[86:87]
	v_cndmask_b32_e64 v100, v223, v100, s[88:89]
	v_cndmask_b32_e64 v99, v223, v99, s[90:91]
	v_cndmask_b32_e64 v98, v223, v98, s[92:93]
	v_cndmask_b32_e64 v97, v223, v97, s[94:95]
	v_cndmask_b32_e64 v96, v223, v96, s[96:97]

; template <int TYPE  >
; __device__ __forceinline__ void attn_item(const Params& P, const int b, const int h, const int qt, LAS unsigned char* lds) {
;     ...
;     constexpr int CH = (KS == 12) ? 3 : 4, NC = KS / CH;
.LBB0_1128:
	s_waitcnt vmcnt(5)
	s_add_i32 s12, s10, 0
	s_barrier
	s_cmp_gt_i32 s11, s3
	s_cbranch_scc1 .LBB0_1132
	v_add_u32_e32 v0, s2, v230
	v_add_u32_e32 v214, 0, v0
	v_xad_u32 v215, v0, 32, 0
	v_xad_u32 v231, v0, 64, 0
	v_xor_b32_e32 v0, 0x60, v0
	v_add_u32_e32 v0, 0, v0
	ds_read_b128 v[66:69], v214
	ds_read_b128 v[70:73], v214 offset:12288
	ds_read_b128 v[200:203], v215
	ds_read_b128 v[236:239], v215 offset:12288
	ds_read_b128 v[146:149], v231
	ds_read_b128 v[150:153], v231 offset:12288
	ds_read_b128 v[154:157], v0
	ds_read_b128 v[158:161], v0 offset:12288
	ds_read_b128 v[192:195], v214 offset:128
	ds_read_b128 v[196:199], v214 offset:12416
	ds_read_b128 v[204:207], v215 offset:128
	ds_read_b128 v[240:243], v215 offset:12416
	s_setprio 1
	s_waitcnt lgkmcnt(10)
	v_mfma_f32_32x32x16_bf16 v[82:97], v[66:69], v[142:145], 0
	v_mfma_f32_32x32x16_bf16 v[66:81], v[70:73], v[142:145], 0
	s_waitcnt lgkmcnt(8)
	v_mfma_f32_32x32x16_bf16 v[82:97], v[200:203], v[138:141], v[82:97]
	v_mfma_f32_32x32x16_bf16 v[66:81], v[236:239], v[138:141], v[66:81]
	s_waitcnt lgkmcnt(6)
	v_mfma_f32_32x32x16_bf16 v[82:97], v[146:149], v[134:137], v[82:97]
	v_mfma_f32_32x32x16_bf16 v[66:81], v[150:153], v[134:137], v[66:81]
	s_setprio 0
	ds_read_b128 v[146:149], v231 offset:128
	ds_read_b128 v[150:153], v231 offset:12416
	ds_read_b128 v[200:203], v0 offset:128
	ds_read_b128 v[236:239], v0 offset:12416
	ds_read_b128 v[244:247], v214 offset:256
	ds_read_b128 v[248:251], v214 offset:12544
	s_setprio 1
	s_waitcnt lgkmcnt(10)
	v_mfma_f32_32x32x16_bf16 v[82:97], v[154:157], v[130:133], v[82:97]
	v_mfma_f32_32x32x16_bf16 v[66:81], v[158:161], v[130:133], v[66:81]
	s_waitcnt lgkmcnt(8)
	v_mfma_f32_32x32x16_bf16 v[82:97], v[192:195], v[126:129], v[82:97]
	v_mfma_f32_32x32x16_bf16 v[66:81], v[196:199], v[126:129], v[66:81]
	s_waitcnt lgkmcnt(6)
	v_mfma_f32_32x32x16_bf16 v[82:97], v[204:207], v[122:125], v[82:97]
	v_mfma_f32_32x32x16_bf16 v[66:81], v[240:243], v[122:125], v[66:81]
	s_setprio 0
	ds_read_b128 v[154:157], v215 offset:256
	ds_read_b128 v[158:161], v215 offset:12544
	ds_read_b128 v[192:195], v231 offset:256
	ds_read_b128 v[196:199], v231 offset:12544
	ds_read_b128 v[204:207], v0 offset:256
	ds_read_b128 v[240:243], v0 offset:12544
	s_setprio 1
	s_waitcnt lgkmcnt(0)
	v_mfma_f32_32x32x16_bf16 v[82:97], v[146:149], v[114:117], v[82:97]
	v_mfma_f32_32x32x16_bf16 v[66:81], v[150:153], v[114:117], v[66:81]
	v_mfma_f32_32x32x16_bf16 v[82:97], v[200:203], v[110:113], v[82:97]
	v_mfma_f32_32x32x16_bf16 v[66:81], v[236:239], v[110:113], v[66:81]
	v_mfma_f32_32x32x16_bf16 v[82:97], v[244:247], v[118:121], v[82:97]
	v_mfma_f32_32x32x16_bf16 v[66:81], v[248:251], v[118:121], v[66:81]
	s_setprio 0
	s_setprio 1
	v_mfma_f32_32x32x16_bf16 v[82:97], v[154:157], v[106:109], v[82:97]
	v_mfma_f32_32x32x16_bf16 v[66:81], v[158:161], v[106:109], v[66:81]
	v_mfma_f32_32x32x16_bf16 v[82:97], v[192:195], v[102:105], v[82:97]
	v_mfma_f32_32x32x16_bf16 v[66:81], v[196:199], v[102:105], v[66:81]
	v_mfma_f32_32x32x16_bf16 v[82:97], v[204:207], v[98:101], v[82:97]
	v_mfma_f32_32x32x16_bf16 v[66:81], v[240:243], v[98:101], v[66:81]
	s_setprio 0
	v_add_u32_e32 v154, s2, v229
	v_add_u32_e32 v0, s2, v228
	v_xor_b32_e32 v155, 64, v154
	v_add_u32_e32 v0, 0, v0
	v_xor_b32_e32 v146, 32, v154
	v_add_u32_e32 v232, 0, v155
	v_xor_b32_e32 v154, 0x60, v154
	s_nop 7
	s_nop 7
	s_nop 3
	v_add_u32_e32 v231, 0, v146
	ds_read_b128 v[150:153], v0 offset:24576
	ds_read_b128 v[146:149], v231
	v_add_u32_e32 v233, 0, v154
	ds_read_b128 v[158:161], v232
	ds_read_b128 v[154:157], v233
	v_max3_f32 v192, v234, v82, v66
	s_nop 0
	v_max3_f32 v192, v192, v83, v67
	s_nop 0
	v_max3_f32 v192, v192, v84, v68
	s_nop 0
	v_max3_f32 v192, v192, v85, v69
	s_nop 0
	v_max3_f32 v192, v192, v86, v70
	s_nop 0
	v_max3_f32 v192, v192, v87, v71
	s_nop 0
	v_max3_f32 v192, v192, v88, v72
	s_nop 0
	v_max3_f32 v192, v192, v89, v73
	s_nop 0
	v_max3_f32 v192, v192, v90, v74
	s_nop 0
	v_max3_f32 v192, v192, v91, v75
	s_nop 0
	v_max3_f32 v192, v192, v92, v76
	s_nop 0
	v_max3_f32 v192, v192, v93, v77
	s_nop 0
	v_max3_f32 v192, v192, v94, v78
	s_nop 0
	v_max3_f32 v192, v192, v95, v79
	s_nop 0
	v_max3_f32 v192, v192, v96, v80
	s_nop 0
	v_max3_f32 v192, v192, v97, v81
	s_nop 0
	s_nop 1
	s_nop 0
	v_mov_b32_e32 v193, v192
	s_nop 1
	v_permlane32_swap_b32_e32 v192, v193
	v_max_f32_e32 v193, v193, v193
	v_max_f32_e32 v192, v192, v192
	v_max_f32_e32 v192, v192, v193
	v_cmp_gt_f32_e32 vcc, v192, v234
	v_mov_b32_e32 v193, v192
	v_pk_add_f32 v[206:207], v[82:83], v[192:193] neg_lo:[0,1] neg_hi:[0,1]
	v_pk_add_f32 v[204:205], v[66:67], v[192:193] neg_lo:[0,1] neg_hi:[0,1]
	v_pk_add_f32 v[202:203], v[84:85], v[192:193] neg_lo:[0,1] neg_hi:[0,1]
	v_pk_add_f32 v[200:201], v[68:69], v[192:193] neg_lo:[0,1] neg_hi:[0,1]
	v_pk_add_f32 v[198:199], v[86:87], v[192:193] neg_lo:[0,1] neg_hi:[0,1]
	v_pk_add_f32 v[196:197], v[70:71], v[192:193] neg_lo:[0,1] neg_hi:[0,1]
	v_pk_add_f32 v[194:195], v[88:89], v[192:193] neg_lo:[0,1] neg_hi:[0,1]
	v_pk_add_f32 v[88:89], v[72:73], v[192:193] neg_lo:[0,1] neg_hi:[0,1]
	v_pk_add_f32 v[86:87], v[90:91], v[192:193] neg_lo:[0,1] neg_hi:[0,1]
	v_pk_add_f32 v[84:85], v[74:75], v[192:193] neg_lo:[0,1] neg_hi:[0,1]
	v_pk_add_f32 v[82:83], v[92:93], v[192:193] neg_lo:[0,1] neg_hi:[0,1]
	v_pk_add_f32 v[74:75], v[76:77], v[192:193] neg_lo:[0,1] neg_hi:[0,1]
	v_pk_add_f32 v[72:73], v[94:95], v[192:193] neg_lo:[0,1] neg_hi:[0,1]
	v_pk_add_f32 v[70:71], v[78:79], v[192:193] neg_lo:[0,1] neg_hi:[0,1]
	v_pk_add_f32 v[68:69], v[96:97], v[192:193] neg_lo:[0,1] neg_hi:[0,1]
	v_pk_add_f32 v[66:67], v[80:81], v[192:193] neg_lo:[0,1] neg_hi:[0,1]
	s_cbranch_vccz .LBB0_1131
; __device__ __forceinline__ float exp2_(float x) { return __builtin_amdgcn_exp2f(x); }
; template <int TYPE  >
; __device__ __forceinline__ void attn_item(const Params& P, const int b, const int h, const int qt, LAS unsigned char* lds) {
;     ...
;                 if (__any(mnew > m_run)) {
;                     const float alpha = exp2_(m_run - mnew);
;                     l_run *= alpha; o0 *= alpha; o1 *= alpha; o2 *= alpha; o3 *= alpha;
;                 }
	v_sub_f32_e32 v76, v234, v192
	v_exp_f32_e32 v76, v76
	s_nop 0
	v_mul_f32_e32 v227, v227, v76
	v_pk_mul_f32 v[64:65], v[64:65], v[76:77] op_sel_hi:[1,0]
	v_pk_mul_f32 v[62:63], v[62:63], v[76:77] op_sel_hi:[1,0]
	v_pk_mul_f32 v[60:61], v[60:61], v[76:77] op_sel_hi:[1,0]
	v_pk_mul_f32 v[58:59], v[58:59], v[76:77] op_sel_hi:[1,0]
	v_pk_mul_f32 v[56:57], v[56:57], v[76:77] op_sel_hi:[1,0]
	v_pk_mul_f32 v[54:55], v[54:55], v[76:77] op_sel_hi:[1,0]
	v_pk_mul_f32 v[52:53], v[52:53], v[76:77] op_sel_hi:[1,0]
	v_pk_mul_f32 v[50:51], v[50:51], v[76:77] op_sel_hi:[1,0]
	v_pk_mul_f32 v[48:49], v[48:49], v[76:77] op_sel_hi:[1,0]
	v_pk_mul_f32 v[46:47], v[46:47], v[76:77] op_sel_hi:[1,0]
	v_pk_mul_f32 v[44:45], v[44:45], v[76:77] op_sel_hi:[1,0]
	v_pk_mul_f32 v[42:43], v[42:43], v[76:77] op_sel_hi:[1,0]
	v_pk_mul_f32 v[40:41], v[40:41], v[76:77] op_sel_hi:[1,0]
	v_pk_mul_f32 v[38:39], v[38:39], v[76:77] op_sel_hi:[1,0]
	v_pk_mul_f32 v[36:37], v[36:37], v[76:77] op_sel_hi:[1,0]
	v_pk_mul_f32 v[34:35], v[34:35], v[76:77] op_sel_hi:[1,0]
	v_pk_mul_f32 v[32:33], v[32:33], v[76:77] op_sel_hi:[1,0]
	v_pk_mul_f32 v[30:31], v[30:31], v[76:77] op_sel_hi:[1,0]
	v_pk_mul_f32 v[28:29], v[28:29], v[76:77] op_sel_hi:[1,0]
	v_pk_mul_f32 v[26:27], v[26:27], v[76:77] op_sel_hi:[1,0]
	v_pk_mul_f32 v[24:25], v[24:25], v[76:77] op_sel_hi:[1,0]
	v_pk_mul_f32 v[22:23], v[22:23], v[76:77] op_sel_hi:[1,0]
	v_pk_mul_f32 v[20:21], v[20:21], v[76:77] op_sel_hi:[1,0]
	v_pk_mul_f32 v[18:19], v[18:19], v[76:77] op_sel_hi:[1,0]
	v_pk_mul_f32 v[16:17], v[16:17], v[76:77] op_sel_hi:[1,0]
	v_pk_mul_f32 v[14:15], v[14:15], v[76:77] op_sel_hi:[1,0]
	v_pk_mul_f32 v[12:13], v[12:13], v[76:77] op_sel_hi:[1,0]
	v_pk_mul_f32 v[10:11], v[10:11], v[76:77] op_sel_hi:[1,0]
	v_pk_mul_f32 v[8:9], v[8:9], v[76:77] op_sel_hi:[1,0]
	v_pk_mul_f32 v[6:7], v[6:7], v[76:77] op_sel_hi:[1,0]
	v_pk_mul_f32 v[4:5], v[4:5], v[76:77] op_sel_hi:[1,0]
	v_pk_mul_f32 v[2:3], v[2:3], v[76:77] op_sel_hi:[1,0]

; #define LAS __attribute__((address_space(3)))
; __device__ __forceinline__ f32x2 pk_sub(f32x2 a, f32x2 b) { f32x2 r; asm("v_pk_add_f32 %0, %1, %2 neg_lo:[0,1] neg_hi:[0,1]" : "=v"(r) : "v"(a), "v"(b)); return r; }
; template <int TYPE  >
; __device__ __forceinline__ void attn_item(const Params& P, const int b, const int h, const int qt, LAS unsigned char* lds) {
;     ...
;     constexpr int CH = (KS == 12) ? 3 : 4, NC = KS / CH;
;     ...
;                 if (TYPE == 1) { const LAS float* fb = (const LAS float*)(lds + so + KREG + VREG + wid * 256) + 8 * hh;
; #pragma unroll
;                     for (int j = 0; j < 8; ++j) {
;                         const f32x2 b0 = *(const LAS f32x2*)(fb + 16 * (j >> 2) + 2 * (j & 3)), b1 = *(const LAS f32x2*)(fb + 32 + 16 * (j >> 2) + 2 * (j & 3));
;                         const f32x2 x0 = pk_sub((f32x2){s0[2 * j], s0[2 * j + 1]}, b0), x1 = pk_sub((f32x2){s1[2 * j], s1[2 * j + 1]}, b1);
;                         s0[2 * j] = x0[0]; s0[2 * j + 1] = x0[1]; s1[2 * j] = x1[0]; s1[2 * j + 1] = x1[1]; }
;                     if (diag) {
; #pragma unroll
;                         for (int i = 0; i < 16; ++i) { const int key = key0 + 16 * (i >> 3) + (i & 7); if (key > tq) s0[i] = -1e30f; if (key + 32 > tq) s1[i] = -1e30f; } } }
.LBB0_1153:
	s_cmp_gt_i32 s16, s11
	s_cbranch_scc1 .Lfx_skipdma
	v_add_u32_e32 v0, s13, v187
	v_add_u32_e32 v70, 0, v0
	v_xad_u32 v74, v0, 32, 0
	ds_read_b128 v[66:69], v70
	ds_read_b128 v[70:73], v70 offset:8192
	ds_read_b128 v[130:133], v74
	ds_read_b128 v[134:137], v74 offset:8192
	v_xad_u32 v74, v0, 64, 0
	ds_read_b128 v[138:141], v74
	ds_read_b128 v[142:145], v74 offset:8192
	v_xor_b32_e32 v74, 0x60, v0
	v_add_u32_e32 v74, 0, v74
	ds_read_b128 v[156:159], v74
	ds_read_b128 v[176:179], v74 offset:8192
	v_xor_b32_e32 v74, 0x80, v0
	v_add_u32_e32 v74, 0, v74
	ds_read_b128 v[180:183], v74
	ds_read_b128 v[198:201], v74 offset:8192
	v_xor_b32_e32 v74, 0xa0, v0
	v_add_u32_e32 v74, 0, v74
	ds_read_b128 v[202:205], v74
	ds_read_b128 v[226:229], v74 offset:8192
	v_xor_b32_e32 v74, 0xc0, v0
	v_xor_b32_e32 v0, 0xe0, v0
	v_add_u32_e32 v74, 0, v74
	v_add_u32_e32 v0, 0, v0
	ds_read_b128 v[230:233], v74
	ds_read_b128 v[234:237], v74 offset:8192
	ds_read_b128 v[238:241], v0
	ds_read_b128 v[242:245], v0 offset:8192
	s_setprio 1
	s_waitcnt lgkmcnt(14)
	v_mfma_f32_32x32x16_bf16 v[82:97], v[66:69], v[98:101], 0
	v_mfma_f32_32x32x16_bf16 v[66:81], v[70:73], v[98:101], 0
	s_waitcnt lgkmcnt(12)
	v_mfma_f32_32x32x16_bf16 v[82:97], v[130:133], v[102:105], v[82:97]
	v_mfma_f32_32x32x16_bf16 v[66:81], v[134:137], v[102:105], v[66:81]
	s_waitcnt lgkmcnt(10)
	v_mfma_f32_32x32x16_bf16 v[82:97], v[138:141], v[106:109], v[82:97]
	v_mfma_f32_32x32x16_bf16 v[66:81], v[142:145], v[106:109], v[66:81]
	s_waitcnt lgkmcnt(8)
	v_mfma_f32_32x32x16_bf16 v[82:97], v[156:159], v[110:113], v[82:97]
	v_mfma_f32_32x32x16_bf16 v[66:81], v[176:179], v[110:113], v[66:81]
	s_setprio 0
	s_setprio 1
	s_waitcnt lgkmcnt(6)
	v_mfma_f32_32x32x16_bf16 v[82:97], v[180:183], v[114:117], v[82:97]
	v_mfma_f32_32x32x16_bf16 v[66:81], v[198:201], v[114:117], v[66:81]
	s_waitcnt lgkmcnt(4)
	v_mfma_f32_32x32x16_bf16 v[82:97], v[202:205], v[118:121], v[82:97]
	v_mfma_f32_32x32x16_bf16 v[66:81], v[226:229], v[118:121], v[66:81]
	s_waitcnt lgkmcnt(2)
	v_mfma_f32_32x32x16_bf16 v[82:97], v[230:233], v[122:125], v[82:97]
	v_mfma_f32_32x32x16_bf16 v[66:81], v[234:237], v[122:125], v[66:81]
	s_waitcnt lgkmcnt(0)
	v_mfma_f32_32x32x16_bf16 v[82:97], v[238:241], v[126:129], v[82:97]
	v_mfma_f32_32x32x16_bf16 v[66:81], v[242:245], v[126:129], v[66:81]
	s_setprio 0
	v_add_u32_e32 v138, s13, v190
	v_add_u32_e32 v0, s13, v189
	v_xor_b32_e32 v139, 64, v138
	v_add_u32_e32 v0, 0, v0
	v_xor_b32_e32 v130, 32, v138
	v_add_u32_e32 v194, 0, v139
	v_xor_b32_e32 v138, 0x60, v138
	s_nop 7
	s_nop 7
	s_nop 3
	v_add_u32_e32 v193, 0, v130
	ds_read_b128 v[134:137], v0 offset:16384
	ds_read_b128 v[130:133], v193
	v_add_u32_e32 v195, 0, v138
	ds_read_b128 v[142:145], v194
	ds_read_b128 v[138:141], v195
	v_add_u32_e32 v156, s13, v191
	v_add_u32_e32 v184, 0x8000, v156
	ds_read2_b64 v[198:201], v184 offset1:1
	ds_read2_b64 v[202:205], v184 offset0:2 offset1:3
	ds_read2_b64 v[226:229], v184 offset0:16 offset1:17
	ds_read2_b64 v[230:233], v184 offset0:18 offset1:19
	ds_read2_b64 v[234:237], v184 offset0:8 offset1:9
	ds_read2_b64 v[238:241], v184 offset0:24 offset1:25
	ds_read2_b64 v[242:245], v184 offset0:10 offset1:11
	ds_read2_b64 v[246:249], v184 offset0:26 offset1:27
	s_cmp_lg_u32 s11, s16
	s_waitcnt lgkmcnt(0)
	v_pk_add_f32 v[82:83], v[82:83], v[198:199] neg_lo:[0,1] neg_hi:[0,1]
	v_pk_add_f32 v[158:159], v[66:67], v[226:227] neg_lo:[0,1] neg_hi:[0,1]
	v_pk_add_f32 v[156:157], v[84:85], v[200:201] neg_lo:[0,1] neg_hi:[0,1]
	v_pk_add_f32 v[84:85], v[68:69], v[228:229] neg_lo:[0,1] neg_hi:[0,1]
	v_pk_add_f32 v[68:69], v[86:87], v[202:203] neg_lo:[0,1] neg_hi:[0,1]
	v_pk_add_f32 v[86:87], v[88:89], v[204:205] neg_lo:[0,1] neg_hi:[0,1]
	v_pk_add_f32 v[160:161], v[70:71], v[230:231] neg_lo:[0,1] neg_hi:[0,1]
	v_pk_add_f32 v[70:71], v[72:73], v[232:233] neg_lo:[0,1] neg_hi:[0,1]
	v_pk_add_f32 v[72:73], v[90:91], v[234:235] neg_lo:[0,1] neg_hi:[0,1]
	v_pk_add_f32 v[88:89], v[92:93], v[236:237] neg_lo:[0,1] neg_hi:[0,1]
	v_pk_add_f32 v[90:91], v[74:75], v[238:239] neg_lo:[0,1] neg_hi:[0,1]
	v_pk_add_f32 v[74:75], v[76:77], v[240:241] neg_lo:[0,1] neg_hi:[0,1]
	v_pk_add_f32 v[76:77], v[94:95], v[242:243] neg_lo:[0,1] neg_hi:[0,1]
	v_pk_add_f32 v[94:95], v[78:79], v[246:247] neg_lo:[0,1] neg_hi:[0,1]
	v_pk_add_f32 v[92:93], v[96:97], v[244:245] neg_lo:[0,1] neg_hi:[0,1]
	v_pk_add_f32 v[78:79], v[80:81], v[248:249] neg_lo:[0,1] neg_hi:[0,1]
	s_cbranch_scc1 .LBB0_1156
	v_cndmask_b32_e64 v66, v82, v223, s[38:39]
	v_cndmask_b32_e64 v158, v158, v223, s[40:41]
	v_cndmask_b32_e64 v82, v66, v82, s[42:43]
	v_cndmask_b32_e64 v83, v223, v83, s[42:43]
	v_cndmask_b32_e64 v159, v159, v223, s[44:45]
	v_cndmask_b32_e64 v156, v156, v223, s[46:47]
	v_cndmask_b32_e64 v84, v84, v223, s[48:49]
	v_cndmask_b32_e64 v157, v157, v223, s[50:51]
	v_cndmask_b32_e64 v85, v85, v223, s[52:53]
	v_cndmask_b32_e64 v68, v68, v223, s[54:55]
	v_cndmask_b32_e64 v160, v160, v223, s[56:57]
	v_cndmask_b32_e64 v69, v69, v223, s[58:59]
	v_cndmask_b32_e64 v161, v161, v223, s[60:61]
	v_cndmask_b32_e64 v86, v86, v223, s[62:63]
	v_cndmask_b32_e64 v70, v70, v223, s[64:65]
	v_cndmask_b32_e64 v87, v87, v223, s[66:67]
	v_cndmask_b32_e64 v71, v71, v223, s[68:69]
	v_cndmask_b32_e64 v72, v72, v223, s[70:71]
	v_cndmask_b32_e64 v90, v90, v223, s[72:73]
	v_cndmask_b32_e64 v73, v73, v223, s[74:75]
	v_cndmask_b32_e64 v91, v91, v223, s[76:77]
	v_cndmask_b32_e64 v88, v88, v223, s[78:79]
	v_cndmask_b32_e64 v74, v74, v223, s[4:5]
	v_cndmask_b32_e64 v89, v89, v223, s[80:81]
	v_cndmask_b32_e64 v75, v75, v223, s[82:83]
	v_cndmask_b32_e64 v76, v76, v223, s[6:7]
	v_cndmask_b32_e64 v94, v94, v223, s[84:85]
	v_cndmask_b32_e64 v77, v77, v223, s[86:87]
	v_cndmask_b32_e64 v95, v95, v223, s[88:89]
	v_cndmask_b32_e64 v92, v92, v223, s[90:91]
	v_cndmask_b32_e64 v78, v78, v223, s[92:93]
	v_cndmask_b32_e64 v93, v93, v223, s[94:95]
	v_cndmask_b32_e64 v79, v79, v223, s[96:97]
